# P2b units remapped so the eight segments of one (batch, head) run on one XCD (shared start states and conv rows hit that XCD's L2)
# speedup vs baseline: 1.0028x; 1.0017x over previous
; template <bool FULL>
; __device__ __forceinline__ void hgrn_seg(const Params& p, unsigned char* lds, int b, int h, int seg) {
;     const int tid = threadIdx.x, lane = tid & 63, w = __builtin_amdgcn_readfirstlane(tid >> 6);
;     const int pk = 16 * w + (lane & 15), tg = lane >> 4;
;     const int vb = w & 3, kh = w >> 2, r = lane & 31, hh = lane >> 5;
;     unsigned char* ws = p.ws;
;     const bf16_t* Q = (const bf16_t*)(ws + WS_Q); const bf16_t* Kk = (const bf16_t*)(ws + WS_K); const bf16_t* V = (const bf16_t*)(ws + WS_V); const bf16_t* Gt = (const bf16_t*)(ws + WS_G);
;     const float* LOGF = (const float*)(ws + WS_LOGF); bf16_t* CAT = (bf16_t*)(ws + WS_CAT);
;     float* SLOC = (float*)(ws + WS_SLOC); float* SDEC = (float*)(ws + WS_SDEC);
;     const int row0 = b * SEQ + seg * SEGL, bh = b * HEADS + h;
; __global__ void __launch_bounds__(512, 2) hymba_fwd(Params p) {
;     ...
;         for (int u = bx; u < NB * HEADS * NSEG; u += G) { hgrn_seg<true>(p, lds, u >> 5, (u >> 3) & 3, u & 7);
;             const int seg = u & 7, ne = seg < 2 ? 2 : (seg < 6 ? 1 : 0), o0 = (int)((0x88765420u >> (4 * seg)) & 15u);
;             for (int k = 0; k < ne; ++k) conv_pair<16>(p, lds, false, 2 * ((u >> 3) * 8 + o0 + k) + (threadIdx.x >> 8)); }
.LBB0_459:
	v_writelane_b32 v247, s96, 42
	s_nop 1
	v_writelane_b32 v247, s97, 43
	v_writelane_b32 v247, s89, 44
	v_writelane_b32 v247, s92, 45
	s_nop 1
	v_writelane_b32 v247, s93, 46
	v_writelane_b32 v247, s88, 47
	s_or_b64 exec, exec, s[4:5]
	s_waitcnt vmcnt(3) lgkmcnt(0)
	v_cndmask_b32_e64 v0, 0, 1, s[28:29]
	v_cmp_ne_u32_e64 s[0:1], 1, v0
	s_andn2_b64 vcc, exec, s[28:29]
	s_nop 0
	v_writelane_b32 v247, s0, 48
	s_barrier
	s_nop 0
	v_writelane_b32 v247, s1, 49
	s_cbranch_vccnz .LBB0_551
	v_mov_b32_e32 v51, 0
	s_add_u32 s0, s64, 0xb7f5e00
	v_lshlrev_b32_e32 v50, 1, v206
	v_writelane_b32 v247, s0, 50
	s_addc_u32 s0, s65, 0
	v_lshlrev_b32_e32 v0, 2, v206
	v_mov_b32_e32 v1, v51
	v_writelane_b32 v247, s0, 51
	v_lshl_add_u64 v[54:55], s[70:71], 0, v[0:1]
	v_lshl_add_u64 v[0:1], s[64:65], 0, v[50:51]
	s_mov_b64 s[0:1], 0x54f5e00
	v_lshl_add_u64 v[56:57], v[0:1], 0, s[0:1]
	s_movk_i32 s0, 0x440
	v_mov_b32_e32 v0, 0x88
	v_mad_u32_u24 v103, v88, s0, v0
	v_mov_b32_e32 v0, 0x110
	v_mad_u32_u24 v104, v88, s0, v0
	v_mov_b32_e32 v0, 0x198
	v_readlane_b32 s44, v247, 16
	v_mad_u32_u24 v105, v88, s0, v0
	v_mov_b32_e32 v0, 0x220
	v_readlane_b32 s48, v247, 20
	v_readlane_b32 s49, v247, 21
	v_readlane_b32 s50, v247, 22
	v_readlane_b32 s51, v247, 23
	v_readlane_b32 s56, v247, 28
	v_readlane_b32 s57, v247, 29
	v_mad_u32_u24 v106, v88, s0, v0
	v_mov_b32_e32 v0, 0x2a8
	v_readlane_b32 s58, v247, 30
	v_readlane_b32 s59, v247, 31
	s_mov_b64 s[48:49], s[56:57]
	v_lshrrev_b32_e32 v2, 5, v206
	s_add_i32 s3, 0, 0x12c00
	v_mad_u32_u24 v107, v88, s0, v0
	v_mov_b32_e32 v0, 0x330
	s_mov_b64 s[50:51], s[58:59]
	v_lshlrev_b32_e32 v100, 2, v2
	v_mad_u32_u24 v108, v88, s0, v0
	v_mov_b32_e32 v0, 0x3b8
	s_add_u32 s86, s50, 0x4200000
	v_lshlrev_b32_e32 v97, 4, v2
	s_movk_i32 s1, 0x110
	v_mad_u32_u24 v109, v88, s0, v0
	v_or_b32_e32 v0, 2, v100
	v_or_b32_e32 v1, 3, v100
	s_addc_u32 s0, s51, 0
	v_cmp_gt_u32_e64 s[16:17], v0, v48
	v_cmp_gt_u32_e64 s[18:19], v1, v48
	v_lshlrev_b32_e32 v113, 9, v0
	v_lshlrev_b32_e32 v114, 9, v1
	v_readlane_b32 s45, v247, 17
	v_readlane_b32 s46, v247, 18
	v_readlane_b32 s47, v247, 19
	v_readlane_b32 s52, v247, 24
	v_readlane_b32 s53, v247, 25
	v_readlane_b32 s54, v247, 26
	v_readlane_b32 s55, v247, 27
	v_writelane_b32 v247, s0, 52
	v_mad_u32_u24 v127, v48, s1, v97
	v_lshl_add_u64 v[0:1], v[176:177], 2, s[64:65]
	s_mov_b64 s[0:1], 0xc7f5e00
	v_lshl_add_u64 v[58:59], v[0:1], 0, s[0:1]
	v_add_u32_e32 v0, 0, v97
	v_add_u32_e32 v129, 0x12c00, v0
	v_mbcnt_hi_u32_b32 v0, -1, v179
	v_or_b32_e32 v3, 16, v49
	v_and_b32_e32 v132, 64, v0
	s_waitcnt vmcnt(2)
	v_or_b32_e32 v4, 32, v49
	v_or_b32_e32 v0, v132, v3
	v_or_b32_e32 v5, 48, v49
	s_add_u32 s0, s64, 0xb807a00
	v_lshlrev_b32_e32 v133, 2, v0
	v_or_b32_e32 v0, v132, v4
	v_or_b32_e32 v101, 8, v100
	v_or_b32_e32 v6, 9, v100
	v_or_b32_e32 v7, 10, v100
	s_waitcnt vmcnt(1)
	v_or_b32_e32 v8, 11, v100
	v_or_b32_e32 v9, 16, v100
	v_or_b32_e32 v10, 17, v100
	v_or_b32_e32 v11, 18, v100
	s_waitcnt vmcnt(0)
	v_or_b32_e32 v12, 19, v100
	v_or_b32_e32 v13, 24, v100
	v_or_b32_e32 v14, 25, v100
	v_or_b32_e32 v15, 26, v100
	v_or_b32_e32 v16, 27, v100
	v_writelane_b32 v247, s0, 53
	s_addc_u32 s0, s65, 0
	v_lshlrev_b32_e32 v134, 2, v0
	v_or_b32_e32 v0, v132, v5
	v_lshl_add_u64 v[52:53], s[82:83], 0, v[50:51]
	s_mov_b32 s87, 0
	v_add_u32_e32 v98, s3, v97
	v_lshlrev_b32_e32 v99, 3, v88
	v_cmp_gt_u32_e64 s[6:7], 16, v206
	v_cmp_lt_u32_e64 s[8:9], 31, v206
	v_cmp_eq_u32_e64 s[10:11], 3, v88
	v_mul_u32_u24_e32 v102, 0x440, v88
	v_mul_u32_u24_e32 v110, 0x110, v48
	v_lshlrev_b32_e32 v111, 3, v2
	v_cmp_gt_u32_e64 s[12:13], v100, v48
	v_cmp_lt_u32_e64 s[14:15], v100, v48
	v_cmp_gt_u32_e64 s[20:21], v101, v48
	v_cmp_gt_u32_e64 s[22:23], v6, v48
	v_cmp_gt_u32_e64 s[24:25], v7, v48
	v_cmp_gt_u32_e64 s[26:27], v8, v48
	v_cmp_gt_u32_e64 s[28:29], v9, v48
	v_cmp_gt_u32_e64 s[30:31], v10, v48
	v_cmp_gt_u32_e64 s[34:35], v11, v48
	v_cmp_gt_u32_e64 s[36:37], v12, v48
	v_cmp_gt_u32_e64 s[38:39], v13, v48
	v_cmp_gt_u32_e64 s[40:41], v14, v48
	v_cmp_gt_u32_e64 s[42:43], v15, v48
	v_lshlrev_b32_e32 v112, 11, v2
	v_lshlrev_b32_e32 v115, 9, v101
	v_lshlrev_b32_e32 v116, 9, v6
	v_lshlrev_b32_e32 v117, 9, v7
	v_lshlrev_b32_e32 v118, 9, v8
	v_lshlrev_b32_e32 v119, 9, v9
	v_lshlrev_b32_e32 v120, 9, v10
	v_lshlrev_b32_e32 v121, 9, v11
	v_lshlrev_b32_e32 v122, 9, v12
	v_lshlrev_b32_e32 v123, 9, v13
	v_lshlrev_b32_e32 v124, 9, v14
	v_lshlrev_b32_e32 v125, 9, v15
	v_lshlrev_b32_e32 v126, 9, v16
	v_lshl_add_u32 v128, v176, 2, s3
	v_writelane_b32 v247, s0, 54
	v_lshlrev_b32_e32 v130, 4, v96
	s_movk_i32 s92, 0x1000
	s_movk_i32 s0, 0x2000
	s_movk_i32 s1, 0x3000
	s_mov_b32 s5, 0x5040100
	v_mov_b32_e32 v131, 0x358637bd
	s_mov_b32 s88, 0x800000
	s_add_i32 s89, 0, 0x1ac00
	s_add_i32 s33, 0, 0x1ec00
	s_mov_b32 s3, 0x96f6000
	v_lshlrev_b32_e32 v135, 2, v0
	s_and_b32 s100, s2, 7
	s_lshl_b32 s100, s100, 5
	s_lshr_b32 s93, s2, 3
	s_add_u32 s100, s100, s93
	s_mov_b32 s93, s100
	s_mov_b32 s96, 0
	s_mov_b32 s97, s100
	v_cmp_gt_u32_e64 s[44:45], v16, v48
	s_mov_b64 s[58:59], s[82:83]
	s_branch .LBB0_462

; #define LDS_BARRIER() do { asm volatile("s_waitcnt lgkmcnt(0)" ::: "memory"); __builtin_amdgcn_s_barrier(); asm volatile("" ::: "memory"); } while (0)
; template <bool FULL>
; __device__ __forceinline__ void hgrn_seg(const Params& p, unsigned char* lds, int b, int h, int seg) {
;     ...
;     if (FULL && seg > 0) {
;         float* dl = (float*)(lds + H_P);
;         for (int idx = tid; idx < seg * DK; idx += 512) dl[idx] = SDEC[(size_t)bh * NSEG * DK + idx];
;         LDS_BARRIER();
;         const float* sl0 = SLOC + (size_t)bh * NSEG * DK * DV + (size_t)(w * 8 * 64 + lane) * 4;
; #pragma unroll 2
;         for (int j = 0; j < seg; ++j) { const float* sl = sl0 + (size_t)j * DK * DV; const float* dj = dl + j * DK + 64 * kh + 4 * hh;
; #pragma unroll
;             for (int a = 0; a < 2; ++a)
; #pragma unroll
;                 for (int g = 0; g < 4; ++g) { const f32x4 d4 = *(const f32x4*)(dj + 32 * a + 8 * g), s4 = *(const f32x4*)(sl + (a * 4 + g) * 256);
; #pragma unroll
;                     for (int i = 0; i < 4; ++i) S[a][4 * g + i] = d4[i] * S[a][4 * g + i] + s4[i]; } }
;         LDS_BARRIER();
; __global__ void __launch_bounds__(512, 2) hymba_fwd(Params p) {
;     ...
;         for (int u = bx; u < NB * HEADS * NSEG; u += G) { hgrn_seg<true>(p, lds, u >> 5, (u >> 3) & 3, u & 7);
.LBB0_466:
	s_or_b64 exec, exec, s[62:63]
	v_readlane_b32 s52, v247, 38
	v_readlane_b32 s54, v247, 40
	s_mul_i32 s47, s96, s54
	s_add_i32 s47, s47, s100
	s_waitcnt lgkmcnt(0)
	s_barrier
	s_and_b32 s62, s47, 7
	s_lshl_b32 s60, s95, 9
	s_and_b32 s65, s51, 0xffffff00
	s_mov_b32 s57, s87
	s_cmp_eq_u32 s62, 1
	v_readlane_b32 s53, v247, 39
	v_readlane_b32 s55, v247, 41
	s_cbranch_scc1 .LBB0_550
	s_add_i32 s66, s66, s67
	s_ashr_i32 s67, s66, 31
	s_and_b32 s62, s50, 6
	s_lshl_b64 s[66:67], s[66:67], 19
	v_readlane_b32 s52, v247, 53
	s_add_u32 s66, s52, s66
	v_readlane_b32 s52, v247, 54
	v_add_u32_e32 v50, s60, v206
	s_addc_u32 s67, s52, s67
	v_mov_b32_e32 v16, 0
	v_lshl_add_u64 v[32:33], v[50:51], 4, s[66:67]
	v_add_u32_e32 v34, s65, v129
	s_mov_b32 s63, 0
	v_mov_b32_e32 v17, v16
	v_mov_b32_e32 v18, v16
	v_mov_b32_e32 v19, v16
	v_mov_b32_e32 v20, v16
	v_mov_b32_e32 v21, v16
	v_mov_b32_e32 v22, v16
	v_mov_b32_e32 v23, v16
	v_mov_b32_e32 v24, v16
	v_mov_b32_e32 v25, v16
	v_mov_b32_e32 v26, v16
	v_mov_b32_e32 v27, v16
	v_mov_b32_e32 v28, v16
	v_mov_b32_e32 v29, v16
	v_mov_b32_e32 v30, v16
	v_mov_b32_e32 v31, v16
	s_waitcnt vmcnt(3)
	v_mov_b32_e32 v0, v16
	v_mov_b32_e32 v1, v16
	v_mov_b32_e32 v2, v16
	v_mov_b32_e32 v3, v16
	s_waitcnt vmcnt(1)
	v_mov_b32_e32 v4, v16
	v_mov_b32_e32 v5, v16
	v_mov_b32_e32 v6, v16
	v_mov_b32_e32 v7, v16
	v_mov_b32_e32 v8, v16
	v_mov_b32_e32 v9, v16
	v_mov_b32_e32 v10, v16
	v_mov_b32_e32 v11, v16
	s_waitcnt vmcnt(0)
	v_mov_b32_e32 v12, v16
	v_mov_b32_e32 v13, v16
	v_mov_b32_e32 v14, v16
	v_mov_b32_e32 v15, v16
